# conversion queue: next claim issued before the tile loads (claim latency off the per-tile chain) at the FFN-up and attention-phase sites; FFN-up idle extras 4, attention-phase extras 2/5
# baseline (speedup 1.0000x reference)
; __global__ void __launch_bounds__(NWAVES * 64, 2) mega_fwd(Args A) {
;     ...
;     const int G = gridDim.x, bx = blockIdx.x;
;     unsigned char* ws = A.ws;
;     for (int u = tid; u < (LDS_BYTES - LDSCTL_OFF) / 4; u += NWAVES * 64) ((LAS unsigned*)(lds + LDSCTL_OFF))[u] = 0u;
;     __syncthreads();
;     XcdBarrier bar = xcd_barrier_post((unsigned*)(ws + WS_CTL) + CW_BAR, (volatile LAS unsigned*)(lds + MISC_OFF) + 8);
;     float* X = (float*)(ws + WS_X); bf16* H = (bf16*)(ws + WS_H); bf16* ACT = (bf16*)(ws + WS_ACT); bf16* PROJ = (bf16*)(ws + WS_PROJ);
;     bf16* Y = (bf16*)(ws + WS_Y); float* MACC = (float*)(ws + WS_MACC); bf16* MB = (bf16*)(ws + WS_MB); float* GO = (float*)(ws + WS_GO);
;     const float* COS = (const float*)(ws + WS_ROPE); const float* SIN = COS + (size_t)NTOK * 32;
;     { int t_ = threadIdx.x; asm volatile("" : "+v"(t_)); const int w_ = __builtin_amdgcn_readfirstlane(t_ >> 6); p0_prologue(A, lds, bx * NWAVES + w_, G * NWAVES, w_, t_ & 63); }
;     conv_until(A, lds, TL_WO1, 0);
;     xcd_barrier(bar);
; #pragma unroll 1
;     for (int step = 0; step < 3 * DEPTH; ++step) {
;         const int l = step / 3, kind = step - 3 * l;
;         unsigned char* wl = ws + WS_W + (size_t)l * LW_END;
;         const unsigned long long* ssq = (const unsigned long long*)(ws + WS_CTL + CTL_SSQ) + (size_t)step * NTOK; unsigned long long* ssq_next = (unsigned long long*)(ws + WS_CTL + CTL_SSQ) + (size_t)(step + 1) * NTOK;
;         if (kind != 1) {
;             { pg8::Gemm g{H, (const bf16*)(wl + (kind == 0 ? LW_WI1 : LW_WI2)), NTOK, NWI, DM}; pg8::StaticOrder S; S.init(NTOK, NWI, G, bx);
;               pg8::EpiSwiglu E{ACT, DFF, ssq};
;               pg8::gemm_phase<pg8::EpiSwiglu, pg8::StaticOrder, true, true>(lds + RING_OFF, g, S, E); }
;             { const int rem1 = ((NTOK / 256) * (NWI / 256)) % G;
;               conv_until(A, lds, l * TL_LAYER + (kind == 0 ? TL_WIN : TL_LAYER), (rem1 != 0 && bx >= rem1) ? 3 : 0); }
;             xcd_barrier(bar);
;         } else {
;             const bool std256 = (G == 256);
;             unsigned char* XB8 = ws + WS_X;
; #pragma unroll 1
;             for (int part = 0; part < 3; ++part) {
;                 bool do16, do8; int i16, n16, g8, c8, i8, n8;
;                 if (std256) { do16 = part == 0 || (part == 1 && bx < 64); i16 = part ? 2 : 0; n16 = part ? 1 : 2;
.LBB0_284:
	v_writelane_b32 v252, s64, 42
	s_nop 1
	v_writelane_b32 v252, s65, 43
	v_writelane_b32 v252, s66, 44
	v_writelane_b32 v252, s67, 45
	v_writelane_b32 v252, s68, 46
	v_writelane_b32 v252, s69, 47
	v_writelane_b32 v252, s70, 48
	v_writelane_b32 v252, s71, 49
	v_writelane_b32 v252, s72, 50
	v_writelane_b32 v252, s73, 51
	v_writelane_b32 v252, s74, 52
	v_writelane_b32 v252, s75, 53
	v_writelane_b32 v252, s76, 54
	v_writelane_b32 v252, s77, 55
	v_writelane_b32 v252, s78, 56
	v_writelane_b32 v252, s79, 57
	s_or_b64 exec, exec, s[0:1]
	s_cmpk_lg_i32 s95, 0x100
	s_cselect_b64 s[0:1], -1, 0
	s_and_b64 s[0:1], s[0:1], exec
	s_cselect_b32 s69, s95, 0x80
	s_add_i32 s4, s97, 0xffffff80
	s_cmpk_lg_i32 s95, 0x100
	s_cselect_b64 s[0:1], -1, 0
	s_and_b64 s[2:3], s[0:1], exec
	s_cselect_b32 s20, s97, s4
	v_readlane_b32 s4, v252, 2
	v_readlane_b32 s18, v252, 16
	v_readlane_b32 s19, v252, 17
	s_add_u32 s74, s18, 0x10000
	s_addc_u32 s2, s19, 0
	v_readlane_b32 s5, v252, 3
	v_readlane_b32 s6, v252, 4
	v_readlane_b32 s7, v252, 5
	v_readlane_b32 s8, v252, 6
	v_readlane_b32 s9, v252, 7
	v_readlane_b32 s10, v252, 8
	v_readlane_b32 s11, v252, 9
	v_readlane_b32 s12, v252, 10
	v_readlane_b32 s13, v252, 11
	v_readlane_b32 s14, v252, 12
	v_readlane_b32 s15, v252, 13
	v_readlane_b32 s16, v252, 14
	v_readlane_b32 s17, v252, 15
	v_writelane_b32 v252, s2, 58
	s_add_u32 s2, s18, 0x35e00000
	s_addc_u32 s3, s19, 0
	s_add_u32 s88, s18, 0x3b600000
	s_addc_u32 s89, s19, 0
	v_writelane_b32 v252, s2, 59
	s_add_u32 s12, s18, 0x45e00000
	s_addc_u32 s13, s19, 0
	v_writelane_b32 v252, s3, 60
	v_writelane_b32 v252, s12, 61
	s_add_u32 s2, s18, 0x4c200000
	v_writelane_b32 v252, s13, 62
	s_addc_u32 s3, s19, 0
	v_writelane_b32 v252, s2, 63
	s_waitcnt vmcnt(15)
	v_mov_b32_e32 v3, 0
	v_mov_b32_e32 v216, 1
	v_writelane_b32 v253, s3, 0
	s_add_u32 s2, s18, 0x4e200000
	s_addc_u32 s3, s19, 0
	v_writelane_b32 v253, s2, 1
	v_mov_b32_e32 v217, 0x7f7f7f7f
	v_mov_b32_e32 v225, 0x43e00000
	v_writelane_b32 v253, s3, 2
	s_add_u32 s2, s18, 0x4fa00000
	s_addc_u32 s3, s19, 0
	v_writelane_b32 v253, s2, 3
	v_mov_b64_e32 v[226:227], 0x2ff
	v_mov_b32_e32 v222, 0x41b17218
	v_writelane_b32 v253, s3, 4
	s_add_u32 s2, s18, 0x4fb00000
	s_addc_u32 s3, s19, 0
	v_writelane_b32 v253, s2, 5
	v_mbcnt_hi_u32_b32 v223, -1, v76
	v_mov_b32_e32 v224, 0xf149f2ca
	v_writelane_b32 v253, s3, 6
	s_add_u32 s2, s18, 0x200000
	v_writelane_b32 v253, s2, 7
	s_addc_u32 s2, s19, 0
	s_cmpk_lt_i32 s97, 0x580
	v_writelane_b32 v253, s2, 8
	s_cselect_b64 s[2:3], -1, 0
	v_writelane_b32 v253, s2, 9
	s_ashr_i32 s21, s97, 31
	s_movk_i32 s75, 0xc0
	v_writelane_b32 v253, s3, 10
	s_lshr_b32 s2, s21, 29
	s_add_i32 s3, s97, s2
	s_ashr_i32 s2, s3, 3
	s_and_b32 s3, s3, -8
	s_sub_i32 s5, s97, s3
	s_ashr_i32 s3, s95, 31
	s_add_u32 s6, s18, 0x4200
	v_writelane_b32 v253, s3, 11
	s_addc_u32 s7, s19, 0
	v_writelane_b32 v253, s6, 12
	s_movk_i32 s76, 0x300
	s_movk_i32 s77, 0x5400
	v_writelane_b32 v253, s7, 13
	s_add_u32 s6, s18, 0x4400
	s_addc_u32 s7, s19, 0
	v_writelane_b32 v253, s6, 14
	s_movk_i32 s81, 0x7fff
	s_mov_b32 s82, 0xffff0000
	v_writelane_b32 v253, s7, 15
	s_add_u32 s6, s18, 0x4500
	s_addc_u32 s7, s19, 0
	v_writelane_b32 v253, s6, 16
	s_movk_i32 s61, 0x1110
	s_movk_i32 s84, 0x15ff
	v_writelane_b32 v253, s7, 17
	s_add_u32 s6, s18, 0x4600
	s_addc_u32 s7, s19, 0
	v_writelane_b32 v253, s6, 18
	s_mov_b32 s85, 0xc3e00000
	s_movk_i32 s33, 0xff
	v_writelane_b32 v253, s7, 19
	s_add_u32 s6, s18, 0x4700
	s_addc_u32 s7, s19, 0
	v_writelane_b32 v253, s6, 20
	s_movk_i32 s66, 0x90
	s_mov_b32 s96, 0x2aaaaaab
	v_writelane_b32 v253, s7, 21
	s_add_u32 s6, s18, 0x4800
	s_addc_u32 s7, s19, 0
	v_writelane_b32 v253, s6, 22
	s_movk_i32 s36, 0x190
	s_movk_i32 s37, 0xff40
	v_writelane_b32 v253, s7, 23
	s_add_u32 s6, s18, 0x4900
	s_addc_u32 s7, s19, 0
	v_writelane_b32 v253, s6, 24
	s_movk_i32 s38, 0x567
	s_movk_i32 s39, 0x1500
	v_writelane_b32 v253, s7, 25
	s_add_u32 s6, s18, 0x4a00
	s_addc_u32 s7, s19, 0
	v_writelane_b32 v253, s6, 26
	s_movk_i32 s56, 0x1800
	s_movk_i32 s57, 0xc80
	v_writelane_b32 v253, s7, 27
	s_add_u32 s6, s18, 0x4b00
	s_addc_u32 s7, s19, 0
	v_writelane_b32 v253, s6, 28
	s_movk_i32 s58, 0x3ff
	s_mov_b32 s80, 0xefa18f08
	v_writelane_b32 v253, s7, 29
	s_add_u32 s6, s18, 0x4c00
	s_addc_u32 s7, s19, 0
	v_writelane_b32 v253, s6, 30
	s_mov_b32 s62, 0
	s_mov_b32 s94, 0x3e000000
	v_writelane_b32 v253, s7, 31
	s_add_u32 s6, s18, 0x4d00
	s_addc_u32 s7, s19, 0
	v_writelane_b32 v253, s6, 32
	s_waitcnt lgkmcnt(0)
	s_barrier
; __global__ void __launch_bounds__(NWAVES * 64, 2) mega_fwd(Args A) {
;     ...
;             const bool std256 = (G == 256);
;             unsigned char* XB8 = ws + WS_X;
; #pragma unroll 1
;             for (int part = 0; part < 3; ++part) {
;                 bool do16, do8; int i16, n16, g8, c8, i8, n8;
;                 if (std256) { do16 = part == 0 || (part == 1 && bx < 64); i16 = part ? 2 : 0; n16 = part ? 1 : 2;
;                               do8 = (part == 1 && bx >= 64) || (part == 2 && bx < 128); g8 = part == 1 ? 192 : 128; c8 = part == 1 ? bx - 64 : bx; i8 = part == 1 ? 0 : 3; n8 = part == 1 ? 2 : 3; }
;                 else { do16 = part == 0; i16 = 0; n16 = 1 << 20; do8 = part == 1; g8 = G; c8 = bx; i8 = 0; n8 = 1 << 20; }
;     ...
;             if (G > 96) { if (bx < 48) gla_scan_unit(lds, ws + WS_GPRE, GO, bx);
;                           else for (int u = bx - 48; u < 256; u += G - 48) att_unit(lds, PROJ, COS, SIN, (const float*)A.in[8] + l * 12, Y, u); }
;             else { for (int u = bx; u < 48; u += G) gla_scan_unit(lds, ws + WS_GPRE, GO, u);
;                    for (int u = bx; u < 256; u += G) att_unit(lds, PROJ, COS, SIN, (const float*)A.in[8] + l * 12, Y, u); }
;             conv_until(A, lds, l * TL_LAYER + TL_WI2, (G > 96 && bx >= 48) ? ((bx - 48) + (G - 48) < 256 ? 1 : 3) : 0);
	v_writelane_b32 v253, s7, 33
	s_add_u32 s6, s18, 0x4e00
	s_addc_u32 s7, s19, 0
	v_writelane_b32 v253, s6, 34
	s_nop 1
	v_writelane_b32 v253, s7, 35
	s_add_u32 s6, s18, 0x4f00
	s_addc_u32 s7, s19, 0
	v_writelane_b32 v253, s6, 36
	s_nop 1
	v_writelane_b32 v253, s7, 37
	s_add_u32 s6, s18, 0x5000
	s_addc_u32 s7, s19, 0
	v_writelane_b32 v253, s6, 38
	s_nop 1
	v_writelane_b32 v253, s7, 39
	s_add_u32 s6, s18, 0x5100
	s_addc_u32 s7, s19, 0
	v_writelane_b32 v253, s6, 40
	s_nop 1
	v_writelane_b32 v253, s7, 41
	s_add_u32 s6, s18, 0x5200
	s_addc_u32 s7, s19, 0
	v_writelane_b32 v253, s6, 42
	s_nop 1
	v_writelane_b32 v253, s7, 43
	s_add_u32 s6, s18, 0x5300
	s_addc_u32 s7, s19, 0
	v_writelane_b32 v253, s6, 44
	s_nop 1
	v_writelane_b32 v253, s7, 45
	s_add_u32 s6, s18, 0x7400
	s_addc_u32 s7, s19, 0
	v_writelane_b32 v253, s6, 46
	s_nop 1
	v_writelane_b32 v253, s7, 47
	s_add_u32 s6, s18, 0x7500
	s_addc_u32 s7, s19, 0
	v_writelane_b32 v253, s6, 48
	s_cmpk_eq_i32 s95, 0x100
	s_nop 0
	v_writelane_b32 v253, s7, 49
	s_cselect_b64 s[6:7], -1, 0
	s_add_u32 s72, s18, 0x2fe00000
	s_addc_u32 s73, s19, 0
	v_writelane_b32 v253, s6, 50
	s_cmp_lt_i32 s97, 64
	s_nop 0
	v_writelane_b32 v253, s7, 51
	s_cselect_b64 s[6:7], -1, 0
	v_writelane_b32 v253, s6, 52
	s_cmp_gt_i32 s97, 63
	s_nop 0
	v_writelane_b32 v253, s7, 53
	s_cselect_b64 s[6:7], -1, 0
	v_writelane_b32 v253, s6, 54
	s_cmpk_lt_i32 s97, 0x80
	s_nop 0
	v_writelane_b32 v253, s7, 55
	s_cselect_b64 s[6:7], -1, 0
	v_writelane_b32 v253, s6, 56
	s_sub_i32 s3, s97, 64
	s_nop 0
	v_writelane_b32 v253, s7, 57
	s_add_u32 s6, s18, 0x3b602400
	v_writelane_b32 v253, s3, 58
	s_addc_u32 s7, s19, 0
	v_writelane_b32 v253, s6, 59
	s_cmpk_gt_i32 s97, 0x7f
	s_nop 0
	v_writelane_b32 v253, s7, 60
	s_cselect_b64 s[6:7], -1, 0
	s_or_b64 s[0:1], s[6:7], s[0:1]
	v_writelane_b32 v253, s0, 61
	s_nop 1
	v_writelane_b32 v253, s1, 62
	s_and_b32 s0, s69, 3
	s_cmp_lg_u32 s0, 0
	s_cselect_b64 s[0:1], -1, 0
	v_writelane_b32 v253, s0, 63
	s_cmpk_lt_i32 s20, 0x200
	s_nop 0
	v_writelane_b32 v254, s1, 0
	s_cselect_b64 s[0:1], -1, 0
	v_writelane_b32 v254, s0, 1
	s_nop 1
	v_writelane_b32 v254, s1, 2
	s_add_u32 s0, s18, 0x46a00000
	s_addc_u32 s1, s19, 0
	v_writelane_b32 v254, s0, 3
	s_and_b32 s4, s20, 3
	s_nop 0
	v_writelane_b32 v254, s1, 4
	s_mul_i32 s0, s4, 0x12000
	s_add_u32 s0, s34, s0
	v_writelane_b32 v254, s0, 5
	v_writelane_b32 v254, s34, 6
	s_addc_u32 s0, s35, 0
	s_lshl_b32 s68, 2, s4
	v_writelane_b32 v254, s35, 7
	v_writelane_b32 v254, s0, 8
	s_lshl_b32 s1, s20, 4
	s_lshl_b32 s0, s69, 4
	s_add_u32 s22, s18, 0x4fc00000
	v_writelane_b32 v254, s0, 9
	s_addc_u32 s23, s19, 0
	s_lshl_b32 s0, s20, 6
	s_and_b32 s0, s0, 0x7c0
	v_writelane_b32 v254, s1, 10
	s_and_b32 s1, s1, 0xfffff800
	s_or_b32 s0, s1, s0
	s_ashr_i32 s1, s0, 31
	v_writelane_b32 v254, s0, 11
	s_bfe_u32 s3, s20, 0x20005
	s_mov_b32 s35, 0
	v_writelane_b32 v254, s1, 12
	s_mul_i32 s0, s3, 0x60
	v_writelane_b32 v254, s20, 13
	s_add_i32 s1, s0, 0x920
	v_writelane_b32 v254, s1, 14
	v_writelane_b32 v254, s0, 15
	s_bitset1_b32 s0, 11
	s_cmpk_lt_i32 s95, 0x61
	v_writelane_b32 v254, s0, 16
	s_cselect_b64 s[0:1], -1, 0
	s_cmpk_gt_i32 s95, 0x60
	v_writelane_b32 v254, s0, 17
	s_cselect_b64 s[6:7], -1, 0
	s_cmp_lt_i32 s97, 48
	v_writelane_b32 v254, s1, 18
	s_cselect_b64 s[0:1], -1, 0
	v_writelane_b32 v254, s0, 19
	s_cmpk_lt_i32 s97, 0x100
	s_nop 0
	v_writelane_b32 v254, s1, 20
	s_cselect_b64 s[0:1], -1, 0
	v_writelane_b32 v254, s0, 21
	s_nop 1
	v_writelane_b32 v254, s1, 22
	s_sub_i32 s0, s97, 48
	v_writelane_b32 v254, s0, 23
	s_cmpk_lt_i32 s97, 0x130
	s_mul_hi_i32 s0, s97, 0x55555556
	s_cselect_b64 s[8:9], -1, 0
	s_lshr_b32 s1, s0, 31
	s_add_i32 s10, s0, s1
	s_mul_i32 s0, s10, -3
	s_add_i32 s0, s0, s97
	v_writelane_b32 v254, s8, 24
	s_lshl_b32 s1, s0, 13
	s_add_i32 s1, s1, 0x8000
	v_writelane_b32 v254, s9, 25
	v_writelane_b32 v254, s1, 26
	s_sub_i32 s1, s95, 48
	v_writelane_b32 v254, s1, 27
	s_lshl_b32 s8, s10, 5
	s_mul_i32 s1, s10, 0x1c4000
	v_writelane_b32 v254, s8, 28
	s_mul_hi_i32 s8, s8, 0xe200
	s_add_u32 s14, s22, s1
	s_addc_u32 s15, s23, s8
	s_add_u32 s8, s14, 0xe000
	v_writelane_b32 v254, s14, 29
	s_addc_u32 s9, s15, 0
	s_lshl_b32 s1, s10, 9
	s_lshl_b32 s0, s0, 6
	v_writelane_b32 v254, s15, 30
	s_and_b32 s11, s1, 0xfffff800
	s_ashr_i32 s1, s0, 31
	v_writelane_b32 v254, s8, 31
	s_cmp_gt_i32 s97, 47
	s_nop 0
	v_writelane_b32 v254, s9, 32
	s_cselect_b64 s[8:9], -1, 0
	v_writelane_b32 v254, s8, 33
	s_mov_b64 s[14:15], s[6:7]
	s_add_i32 s6, s97, s95
	s_addk_i32 s6, 0xffa0
	v_writelane_b32 v254, s9, 34
	s_cmpk_lt_i32 s6, 0x100
	s_cselect_b32 s8, 2, 5
	v_writelane_b32 v254, s14, 35
	s_and_b64 s[6:7], s[14:15], exec
	s_cselect_b32 s6, s8, 0
	v_writelane_b32 v254, s15, 36
	v_writelane_b32 v254, s6, 37
	s_add_u32 s6, s18, 0x47600000
	v_writelane_b32 v254, s6, 38
	s_addc_u32 s6, s19, 0
	v_writelane_b32 v254, s6, 39
	s_lshl_b32 s14, s95, 5
	s_lshl_b32 s6, s5, 5
	s_cmp_lt_i32 s5, 0
	s_movk_i32 s7, 0xb1
; __global__ void __launch_bounds__(NWAVES * 64, 2) mega_fwd(Args A) {
;     ...
;     for (int step = 0; step < 3 * DEPTH; ++step) {
;         const int l = step / 3, kind = step - 3 * l;
;         unsigned char* wl = ws + WS_W + (size_t)l * LW_END;
;         const unsigned long long* ssq = (const unsigned long long*)(ws + WS_CTL + CTL_SSQ) + (size_t)step * NTOK; unsigned long long* ssq_next = (unsigned long long*)(ws + WS_CTL + CTL_SSQ) + (size_t)(step + 1) * NTOK;
;         if (kind != 1) {
;             { pg8::Gemm g{H, (const bf16*)(wl + (kind == 0 ? LW_WI1 : LW_WI2)), NTOK, NWI, DM}; pg8::StaticOrder S; S.init(NTOK, NWI, G, bx);
;               pg8::EpiSwiglu E{ACT, DFF, ssq};
;               pg8::gemm_phase<pg8::EpiSwiglu, pg8::StaticOrder, true, true>(lds + RING_OFF, g, S, E); }
;             { const int rem1 = ((NTOK / 256) * (NWI / 256)) % G;
;               conv_until(A, lds, l * TL_LAYER + (kind == 0 ? TL_WIN : TL_LAYER), (rem1 != 0 && bx >= rem1) ? 3 : 0); }
	s_cselect_b32 s7, s7, 0xb0
	s_mul_i32 s7, s5, s7
	s_mul_i32 s5, s5, 33
	s_cselect_b32 s5, s5, s6
	s_add_i32 s7, s7, s2
	s_mul_hi_i32 s6, s7, 0x2e8ba2e9
	s_lshr_b32 s8, s6, 31
	s_ashr_i32 s6, s6, 6
	s_add_i32 s6, s6, s8
	s_mul_i32 s8, s6, 0x160
	s_sub_i32 s7, s7, s8
	s_bfe_u32 s8, s7, 0x3001c
	s_add_i32 s8, s7, s8
	s_and_b32 s9, s8, 0xfff8
	s_sub_i32 s7, s7, s9
	s_lshl_b32 s6, s6, 3
	s_sext_i32_i16 s8, s8
	s_sext_i32_i16 s7, s7
	s_add_i32 s16, s6, s7
	s_ashr_i32 s6, s8, 3
	v_writelane_b32 v254, s6, 40
	s_lshr_b32 s6, s8, 3
	s_bfe_i64 s[6:7], s[6:7], 0x100000
	s_lshl_b64 s[6:7], s[6:7], 20
	v_writelane_b32 v254, s6, 41
	s_ashr_i32 s17, s16, 31
	s_nop 0
	v_writelane_b32 v254, s7, 42
	s_mov_b32 s6, s16
	v_writelane_b32 v254, s6, 43
	s_nop 1
	v_writelane_b32 v254, s7, 44
	s_lshl_b64 s[6:7], s[16:17], 20
	s_add_u32 s6, s90, s6
	s_addc_u32 s7, s91, s7
	s_add_u32 s8, s6, 0x80000
	s_addc_u32 s9, s7, 0
	v_writelane_b32 v254, s8, 45
	s_nop 1
	v_writelane_b32 v254, s9, 46
	s_add_u32 s8, s6, 0x2000
	v_writelane_b32 v254, s6, 47
	s_addc_u32 s9, s7, 0
	s_add_i32 s2, s5, s2
	s_ashr_i32 s5, s2, 31
	s_lshr_b32 s5, s5, 26
	s_add_i32 s5, s2, s5
	v_writelane_b32 v254, s7, 48
	s_and_b32 s6, s5, 0xffc0
	s_sub_i32 s2, s2, s6
	s_bfe_i32 s6, s2, 0x80000
	s_bfe_u32 s6, s6, 0x3000c
	s_add_i32 s6, s2, s6
	s_and_b32 s7, s6, 0xf8
	s_sub_i32 s2, s2, s7
	s_ashr_i32 s5, s5, 6
	s_lshl_b32 s5, s5, 3
	s_sext_i32_i8 s2, s2
	s_add_i32 s5, s5, s2
	s_bfe_i32 s2, s6, 0x80000
	v_writelane_b32 v254, s8, 49
	s_sext_i32_i16 s2, s2
	s_ashr_i32 s6, s2, 3
	v_writelane_b32 v254, s9, 50
	s_lshr_b32 s2, s2, 3
	v_writelane_b32 v254, s6, 51
	s_bfe_i64 s[6:7], s[2:3], 0x100000
	v_writelane_b32 v254, s6, 52
	s_mul_hi_i32 s2, s5, 0x60000
	s_nop 0
	v_writelane_b32 v254, s7, 53
	v_writelane_b32 v254, s5, 54
	s_mul_i32 s5, s5, 0x60000
	s_add_u32 s6, s12, s5
	s_addc_u32 s7, s13, s2
	s_add_u32 s8, s6, 0x30000
	s_addc_u32 s9, s7, 0
	v_writelane_b32 v254, s8, 55
	s_nop 1
	v_writelane_b32 v254, s9, 56
	s_add_u32 s8, s6, 0x2000
	v_writelane_b32 v254, s6, 57
	s_addc_u32 s9, s7, 0
	s_abs_i32 s2, s95
	v_cvt_f32_u32_e32 v1, s2
	v_writelane_b32 v254, s7, 58
	s_sub_i32 s5, 0, s2
	v_writelane_b32 v254, s8, 59
	v_rcp_iflag_f32_e32 v1, v1
	s_nop 0
	v_writelane_b32 v254, s9, 60
	v_mul_f32_e32 v1, 0x4f7ffffe, v1
	v_cvt_u32_f32_e32 v1, v1
	s_nop 0
	v_readfirstlane_b32 s6, v1
	s_mul_i32 s5, s5, s6
	s_mul_hi_u32 s5, s6, s5
	s_add_i32 s6, s6, s5
	s_mul_hi_u32 s5, s6, 0x580
	s_mul_i32 s5, s5, s2
	s_sub_i32 s5, 0x580, s5
	s_sub_i32 s6, s5, s2
	s_cmp_ge_u32 s5, s2
	s_cselect_b32 s5, s6, s5
	s_sub_i32 s6, s5, s2
	s_cmp_ge_u32 s5, s2
	s_cselect_b32 s2, s6, s5
	s_cmp_lg_u32 s2, 0
	s_cselect_b64 s[6:7], -1, 0
	s_cmp_ge_i32 s97, s2
	s_cselect_b64 s[8:9], -1, 0
	s_and_b64 s[6:7], s[6:7], s[8:9]
	s_mul_i32 s2, s4, 0xc0
	v_writelane_b32 v254, s6, 61
	s_and_b64 s[4:5], s[6:7], exec
	s_cselect_b32 s4, 4, 0
	v_writelane_b32 v254, s7, 62
	v_writelane_b32 v255, s2, 0
	s_lshl_b32 s2, s2, 1
	v_writelane_b32 v254, s4, 63
	s_add_u32 s4, s88, s2
	s_addc_u32 s5, s89, 0
	v_writelane_b32 v255, s4, 1
	s_and_b32 s2, s10, 3
	s_mulk_i32 s2, 0x300
	v_writelane_b32 v255, s5, 2
	s_mul_i32 s4, s11, 0xc00
	s_lshl_b32 s5, s97, 6
	s_or_b32 s2, s4, s2
	s_lshl_b64 s[0:1], s[0:1], 2
	v_writelane_b32 v255, s5, 3
	s_lshl_b32 s5, s95, 6
	s_mul_hi_i32 s4, s11, 0xc00
	s_add_u32 s0, s2, s0
	s_addc_u32 s1, s4, s1
	s_add_u32 s0, s18, s0
	v_writelane_b32 v255, s5, 4
	s_addc_u32 s1, s19, s1
	v_writelane_b32 v255, s0, 5
	s_mul_i32 s2, s95, 0x18000
	s_add_i32 s93, 0, 0x20180
	v_writelane_b32 v255, s1, 6
	s_mul_i32 s0, s3, 0xc0
	s_mul_hi_i32 s3, s14, 0xc00
	v_writelane_b32 v255, s2, 7
	s_lshl_b32 s1, s97, 9
	s_lshl_b32 s0, s0, 1
	v_writelane_b32 v255, s3, 8
	s_mul_i32 s2, s95, 0xa8000
	v_writelane_b32 v255, s14, 9
	s_mul_hi_i32 s3, s14, 0x5400
	v_writelane_b32 v255, s2, 10
	s_add_i32 s60, 0, 0x20184
	v_mov_b32_e32 v1, 0x358637bd
	v_writelane_b32 v255, s3, 11
	v_writelane_b32 v255, s1, 12
	s_lshl_b32 s1, s95, 11
	v_writelane_b32 v255, s1, 13
	s_lshl_b32 s1, s95, 4
	v_writelane_b32 v255, s1, 14
	s_lshl_b32 s1, s95, 10
	v_writelane_b32 v255, s1, 15
	s_lshl_b32 s1, s95, 9
	v_writelane_b32 v255, s1, 16
	s_add_i32 s1, 0, 0x20160
	v_writelane_b32 v255, s1, 17
	s_add_i32 s1, 0, 0x20164
	v_writelane_b32 v255, s1, 18
	s_add_i32 s1, 0, 0x2d00
	v_writelane_b32 v255, s1, 19
	v_writelane_b32 v255, s0, 20
	s_add_i32 s64, 0, 0x12600
	s_nop 0
	v_writelane_b32 v255, s1, 21
	s_add_i32 s0, 0, 0xf000
	v_writelane_b32 v255, s0, 22
	s_add_i32 s0, 0, 0x8800
	v_writelane_b32 v255, s0, 23
	v_writelane_b32 v255, s90, 24
	s_nop 1
	v_writelane_b32 v255, s91, 25
	v_writelane_b32 v255, s69, 26
	v_writelane_b32 v255, s88, 27
	s_nop 1
	v_writelane_b32 v255, s89, 28
	v_writelane_b32 v255, s21, 29
	v_writelane_b32 v255, s22, 30
	v_writelane_b32 v255, s23, 31
	v_writelane_b32 v255, s93, 32
	v_writelane_b32 v255, s60, 33
	v_writelane_b32 v255, s92, 34
	s_nop 1
	v_writelane_b32 v255, s93, 35
	s_branch .LBB0_287

; #define LAS __attribute__((address_space(3)))
; __device__ __forceinline__ unsigned pk2(float lo, float hi) { return f2bf(lo) | (f2bf(hi) << 16); }
; __device__ __forceinline__ void tr_to_lds(LAS unsigned* T, int tid, const f32x4 (&v)[8][2]) {
;     const int c4 = (tid & 15) + 16 * ((tid >> 6) & 1), rp = ((tid >> 4) & 3) + 4 * (tid >> 7);
; #pragma unroll
;     for (int i = 0; i < 8; ++i)
; #pragma unroll
;         for (int j = 0; j < 4; ++j) T[(4 * c4 + j) * 132 + 16 * i + rp] = pk2(v[i][0][j], v[i][1][j]);
; __device__ __forceinline__ void conv_until(const Args& A, LAS unsigned char* lds, int limit, int extra) {
;     ...
;     f32x4 v[8][2]; TrJob jb; int t, k0, n0;
;     conv_job(A, (int)T, jb, t); tr_load(jb, t, tid, v, k0, n0);
; #pragma unroll 1
;     for (;;) {
;         tr_to_lds(Tl, tid, v);
.LBB0_345:
	v_and_b32_e32 v69, -4, v71
	v_ashrrev_i32_e32 v71, 4, v2
	v_bfe_u32 v68, v2, 4, 2
	s_cmp_lg_u32 s31, 0
	v_bfi_b32 v71, -8, v71, v2
	v_lshrrev_b32_e32 v2, 3, v2
	s_cselect_b64 s[4:5], -1, 0
	v_lshlrev_b32_e32 v68, 2, v68
	v_lshlrev_b32_e32 v69, 2, v69
	v_and_or_b32 v79, v2, 7, v70
	s_cmp_lg_u64 s[4:5], 0
	v_readlane_b32 s4, v254, 63
	v_add3_u32 v68, 0, v68, v69
	v_mul_u32_u24_e32 v69, 0x210, v77
	v_lshl_add_u32 v2, v71, 4, 0
	v_mul_u32_u24_e32 v70, 0x210, v79
	s_subb_u32 s21, s4, 0
	v_lshlrev_b32_e32 v80, 3, v71
	v_or_b32_e32 v81, 8, v79
	v_or_b32_e32 v82, 16, v79
	v_or_b32_e32 v83, 24, v79
	v_or_b32_e32 v84, 32, v79
	v_or_b32_e32 v85, 40, v79
	v_or_b32_e32 v86, 48, v79
	v_or_b32_e32 v87, 56, v79
	v_add_u32_e32 v88, v68, v69
	v_add_u32_e32 v89, v2, v70
	s_mov_b32 s63, 0
	s_branch .LBB0_347

; #define LAS __attribute__((address_space(3)))
; __device__ __forceinline__ unsigned pk2(float lo, float hi) { return f2bf(lo) | (f2bf(hi) << 16); }
; __device__ __forceinline__ void tr_to_lds(LAS unsigned* T, int tid, const f32x4 (&v)[8][2]) {
;     const int c4 = (tid & 15) + 16 * ((tid >> 6) & 1), rp = ((tid >> 4) & 3) + 4 * (tid >> 7);
; #pragma unroll
;     for (int i = 0; i < 8; ++i)
; #pragma unroll
;         for (int j = 0; j < 4; ++j) T[(4 * c4 + j) * 132 + 16 * i + rp] = pk2(v[i][0][j], v[i][1][j]);
; __device__ __forceinline__ void conv_until(const Args& A, LAS unsigned char* lds, int limit, int extra) {
;     ...
;     for (;;) {
;         tr_to_lds(Tl, tid, v);
;         if (tid == 0) known = conv_claim(ctr, slot, limit, extra, known, false);
.LBB0_347:
	s_waitcnt vmcnt(15)
	v_bfe_u32 v2, v4, 16, 1
	v_add3_u32 v2, v4, v2, s81
	s_waitcnt vmcnt(14)
	v_bfe_u32 v68, v8, 16, 1
	v_lshrrev_b32_e32 v2, 16, v2
	v_add3_u32 v68, v8, v68, s81
	v_and_or_b32 v2, v68, s82, v2
	v_bfe_u32 v68, v5, 16, 1
	v_add3_u32 v68, v5, v68, s81
	v_bfe_u32 v69, v9, 16, 1
	v_lshrrev_b32_e32 v68, 16, v68
	v_add3_u32 v69, v9, v69, s81
	v_and_or_b32 v68, v69, s82, v68
	v_bfe_u32 v69, v6, 16, 1
	v_add3_u32 v69, v6, v69, s81
	v_bfe_u32 v70, v10, 16, 1
	v_lshrrev_b32_e32 v69, 16, v69
	v_add3_u32 v70, v10, v70, s81
	v_and_or_b32 v69, v70, s82, v69
	v_bfe_u32 v70, v7, 16, 1
	v_add3_u32 v70, v7, v70, s81
	v_bfe_u32 v71, v11, 16, 1
	v_lshrrev_b32_e32 v70, 16, v70
	v_add3_u32 v71, v11, v71, s81
	v_and_or_b32 v70, v71, s82, v70
	s_waitcnt vmcnt(13)
	v_bfe_u32 v71, v12, 16, 1
	v_add3_u32 v71, v12, v71, s81
	s_waitcnt vmcnt(12)
	v_bfe_u32 v72, v16, 16, 1
	v_lshrrev_b32_e32 v71, 16, v71
	v_add3_u32 v72, v16, v72, s81
	v_and_or_b32 v71, v72, s82, v71
	ds_write2_b32 v88, v2, v71 offset1:16
	v_bfe_u32 v2, v13, 16, 1
	v_add3_u32 v2, v13, v2, s81
	v_bfe_u32 v71, v17, 16, 1
	v_lshrrev_b32_e32 v2, 16, v2
	v_add3_u32 v71, v17, v71, s81
	v_and_or_b32 v2, v71, s82, v2
	ds_write2_b32 v88, v68, v2 offset0:132 offset1:148
	v_bfe_u32 v2, v14, 16, 1
	v_add3_u32 v2, v14, v2, s81
	v_bfe_u32 v68, v18, 16, 1
	v_lshrrev_b32_e32 v2, 16, v2
	v_add3_u32 v68, v18, v68, s81
	v_and_or_b32 v2, v68, s82, v2
	v_add_u32_e32 v68, 0x400, v88
	ds_write2_b32 v68, v69, v2 offset0:8 offset1:24
	v_bfe_u32 v2, v15, 16, 1
	v_add3_u32 v2, v15, v2, s81
	v_bfe_u32 v69, v19, 16, 1
	v_lshrrev_b32_e32 v2, 16, v2
	v_add3_u32 v69, v19, v69, s81
	v_and_or_b32 v2, v69, s82, v2
	ds_write2_b32 v68, v70, v2 offset0:140 offset1:156
	s_waitcnt vmcnt(11)
	v_bfe_u32 v2, v20, 16, 1
	v_add3_u32 v2, v20, v2, s81
	s_waitcnt vmcnt(10)
	v_bfe_u32 v69, v24, 16, 1
	v_lshrrev_b32_e32 v2, 16, v2
	v_add3_u32 v69, v24, v69, s81
	v_and_or_b32 v2, v69, s82, v2
	v_bfe_u32 v69, v21, 16, 1
	v_add3_u32 v69, v21, v69, s81
	v_bfe_u32 v70, v25, 16, 1
	v_lshrrev_b32_e32 v69, 16, v69
	v_add3_u32 v70, v25, v70, s81
	v_and_or_b32 v69, v70, s82, v69
	v_bfe_u32 v70, v22, 16, 1
	v_add3_u32 v70, v22, v70, s81
	v_bfe_u32 v71, v26, 16, 1
	v_lshrrev_b32_e32 v70, 16, v70
	v_add3_u32 v71, v26, v71, s81
	v_and_or_b32 v70, v71, s82, v70
	v_bfe_u32 v71, v23, 16, 1
	v_add3_u32 v71, v23, v71, s81
	v_bfe_u32 v72, v27, 16, 1
	v_lshrrev_b32_e32 v71, 16, v71
	v_add3_u32 v72, v27, v72, s81
	v_and_or_b32 v71, v72, s82, v71
	s_waitcnt vmcnt(9)
	v_bfe_u32 v72, v28, 16, 1
	v_add3_u32 v72, v28, v72, s81
	s_waitcnt vmcnt(8)
	v_bfe_u32 v73, v32, 16, 1
	v_lshrrev_b32_e32 v72, 16, v72
	v_add3_u32 v73, v32, v73, s81
	v_and_or_b32 v72, v73, s82, v72
	ds_write2_b32 v88, v2, v72 offset0:32 offset1:48
	v_bfe_u32 v2, v29, 16, 1
	v_add3_u32 v2, v29, v2, s81
	v_bfe_u32 v72, v33, 16, 1
	v_lshrrev_b32_e32 v2, 16, v2
	v_add3_u32 v72, v33, v72, s81
	v_and_or_b32 v2, v72, s82, v2
	ds_write2_b32 v88, v69, v2 offset0:164 offset1:180
	v_bfe_u32 v2, v30, 16, 1
	v_add3_u32 v2, v30, v2, s81
	v_bfe_u32 v69, v34, 16, 1
	v_lshrrev_b32_e32 v2, 16, v2
	v_add3_u32 v69, v34, v69, s81
	v_and_or_b32 v2, v69, s82, v2
	ds_write2_b32 v68, v70, v2 offset0:40 offset1:56
	v_bfe_u32 v2, v31, 16, 1
	v_add3_u32 v2, v31, v2, s81
	v_bfe_u32 v69, v35, 16, 1
	v_lshrrev_b32_e32 v2, 16, v2
	v_add3_u32 v69, v35, v69, s81
	v_and_or_b32 v2, v69, s82, v2
	ds_write2_b32 v68, v71, v2 offset0:172 offset1:188
	s_waitcnt vmcnt(7)
	v_bfe_u32 v2, v36, 16, 1
	v_add3_u32 v2, v36, v2, s81
	s_waitcnt vmcnt(6)
	v_bfe_u32 v69, v40, 16, 1
	v_lshrrev_b32_e32 v2, 16, v2
	v_add3_u32 v69, v40, v69, s81
	v_and_or_b32 v2, v69, s82, v2
	v_bfe_u32 v69, v37, 16, 1
	v_add3_u32 v69, v37, v69, s81
	v_bfe_u32 v70, v41, 16, 1
	v_lshrrev_b32_e32 v69, 16, v69
	v_add3_u32 v70, v41, v70, s81
	v_and_or_b32 v69, v70, s82, v69
	v_bfe_u32 v70, v38, 16, 1
	v_add3_u32 v70, v38, v70, s81
	v_bfe_u32 v71, v42, 16, 1
	v_lshrrev_b32_e32 v70, 16, v70
	v_add3_u32 v71, v42, v71, s81
	v_and_or_b32 v70, v71, s82, v70
	v_bfe_u32 v71, v39, 16, 1
	v_add3_u32 v71, v39, v71, s81
	v_bfe_u32 v72, v43, 16, 1
	v_lshrrev_b32_e32 v71, 16, v71
	v_add3_u32 v72, v43, v72, s81
	v_and_or_b32 v71, v72, s82, v71
	s_waitcnt vmcnt(5)
	v_bfe_u32 v72, v44, 16, 1
	v_add3_u32 v72, v44, v72, s81
	s_waitcnt vmcnt(4)
	v_bfe_u32 v73, v48, 16, 1
	v_lshrrev_b32_e32 v72, 16, v72
	v_add3_u32 v73, v48, v73, s81
	v_and_or_b32 v72, v73, s82, v72
	ds_write2_b32 v88, v2, v72 offset0:64 offset1:80
	v_bfe_u32 v2, v45, 16, 1
	v_add3_u32 v2, v45, v2, s81
	v_bfe_u32 v72, v49, 16, 1
	v_lshrrev_b32_e32 v2, 16, v2
	v_add3_u32 v72, v49, v72, s81
	v_and_or_b32 v2, v72, s82, v2
	ds_write2_b32 v88, v69, v2 offset0:196 offset1:212
	v_bfe_u32 v2, v46, 16, 1
	v_add3_u32 v2, v46, v2, s81
	v_bfe_u32 v69, v50, 16, 1
	v_lshrrev_b32_e32 v2, 16, v2
	v_add3_u32 v69, v50, v69, s81
	v_and_or_b32 v2, v69, s82, v2
	ds_write2_b32 v68, v70, v2 offset0:72 offset1:88
	v_bfe_u32 v2, v47, 16, 1
	v_add3_u32 v2, v47, v2, s81
	v_bfe_u32 v69, v51, 16, 1
	v_lshrrev_b32_e32 v2, 16, v2
	v_add3_u32 v69, v51, v69, s81
	v_and_or_b32 v2, v69, s82, v2
	ds_write2_b32 v68, v71, v2 offset0:204 offset1:220
	s_waitcnt vmcnt(3)
	v_bfe_u32 v2, v52, 16, 1
	v_add3_u32 v2, v52, v2, s81
	s_waitcnt vmcnt(2)
	v_bfe_u32 v69, v56, 16, 1
	v_lshrrev_b32_e32 v2, 16, v2
	v_add3_u32 v69, v56, v69, s81
	v_and_or_b32 v2, v69, s82, v2
	v_bfe_u32 v69, v53, 16, 1
	v_add3_u32 v69, v53, v69, s81
	v_bfe_u32 v70, v57, 16, 1
	v_lshrrev_b32_e32 v69, 16, v69
	v_add3_u32 v70, v57, v70, s81
	v_and_or_b32 v69, v70, s82, v69
	v_bfe_u32 v70, v54, 16, 1
	v_add3_u32 v70, v54, v70, s81
	v_bfe_u32 v71, v58, 16, 1
	v_lshrrev_b32_e32 v70, 16, v70
	v_add3_u32 v71, v58, v71, s81
	v_and_or_b32 v70, v71, s82, v70
	v_bfe_u32 v71, v55, 16, 1
	v_add3_u32 v71, v55, v71, s81
	v_bfe_u32 v72, v59, 16, 1
	v_lshrrev_b32_e32 v71, 16, v71
	v_add3_u32 v72, v59, v72, s81
	v_and_or_b32 v71, v72, s82, v71
	s_waitcnt vmcnt(1)
	v_bfe_u32 v72, v60, 16, 1
	v_add3_u32 v72, v60, v72, s81
	s_waitcnt vmcnt(0)
	v_bfe_u32 v73, v64, 16, 1
	v_lshrrev_b32_e32 v72, 16, v72
	v_add3_u32 v73, v64, v73, s81
	v_and_or_b32 v72, v73, s82, v72
	ds_write2_b32 v88, v2, v72 offset0:96 offset1:112
	v_bfe_u32 v2, v61, 16, 1
	v_add3_u32 v2, v61, v2, s81
	v_bfe_u32 v72, v65, 16, 1
	v_lshrrev_b32_e32 v2, 16, v2
	v_add3_u32 v72, v65, v72, s81
	v_and_or_b32 v2, v72, s82, v2
	ds_write2_b32 v88, v69, v2 offset0:228 offset1:244
	v_bfe_u32 v2, v62, 16, 1
	v_add3_u32 v2, v62, v2, s81
	v_bfe_u32 v69, v66, 16, 1
	v_lshrrev_b32_e32 v2, 16, v2
	v_add3_u32 v69, v66, v69, s81
	v_and_or_b32 v2, v69, s82, v2
	ds_write2_b32 v68, v70, v2 offset0:104 offset1:120
	v_bfe_u32 v2, v63, 16, 1
	v_add3_u32 v2, v63, v2, s81
	v_bfe_u32 v69, v67, 16, 1
	v_lshrrev_b32_e32 v2, 16, v2
	v_add3_u32 v69, v67, v69, s81
	s_mov_b32 s24, s15
	s_mov_b32 s30, s14
	s_mov_b64 s[6:7], s[0:1]
	s_mov_b32 s22, s19
	s_mov_b32 s25, s34
	s_mov_b32 s23, s20
	v_and_or_b32 v2, v69, s82, v2
	ds_write2_b32 v68, v71, v2 offset0:236 offset1:252
	s_and_saveexec_b64 s[4:5], s[2:3]
	s_cbranch_execz .LBB0_353
; #define LAS __attribute__((address_space(3)))
; __device__ __forceinline__ unsigned conv_claim(unsigned* ctr, volatile LAS unsigned* slot, int limit, int extra, unsigned known, bool peek) {
;     if (peek) known = __hip_atomic_load(ctr, __ATOMIC_RELAXED, __HIP_MEMORY_SCOPE_AGENT);
;     const bool need = (int)known < limit, opt = !need && extra > 0 && (int)known < TL_ALL;
;     unsigned T = 0xffffffffu;
;     if (need || opt) { T = __hip_atomic_fetch_add(ctr, 1u, __ATOMIC_RELAXED, __HIP_MEMORY_SCOPE_AGENT); known = T + 1u; if ((int)T >= TL_ALL) T = 0xffffffffu; }
;     slot[0] = T; slot[1] = need ? 0u : 1u;
;     return known;
	s_cmp_lg_u32 s63, 0
	s_cbranch_scc0 .Lca347_orig
	s_mov_b32 s63, 0
	s_mov_b64 s[8:9], exec
	s_cmp_lg_u32 s65, 0
	s_cselect_b64 vcc, exec, 0
	v_mov_b32_e32 v2, 0
	s_waitcnt vmcnt(0)
	v_mov_b32_e32 v68, v142
	s_branch .Lca347_join
.Lca347_orig:
	s_cmp_gt_i32 s21, 0
	s_movk_i32 s0, 0x2fa0
	s_cselect_b64 s[8:9], -1, 0
	v_cmp_gt_i32_e64 s[0:1], s0, v76
	v_cmp_gt_i32_e32 vcc, s59, v76
	s_and_b64 s[0:1], s[0:1], s[8:9]
	s_or_b64 s[0:1], vcc, s[0:1]
	v_mov_b32_e32 v2, -1
	s_and_saveexec_b64 s[8:9], s[0:1]
	s_cbranch_execz .LBB0_352
	s_mov_b64 s[12:13], exec
	v_mbcnt_lo_u32_b32 v2, s12, 0
	v_mbcnt_hi_u32_b32 v2, s13, v2
	v_cmp_eq_u32_e64 s[0:1], 0, v2
	s_and_saveexec_b64 s[10:11], s[0:1]
	s_cbranch_execz .LBB0_351
	s_bcnt1_i32_b64 s0, s[12:13]
	v_mov_b32_e32 v68, s0
	v_readlane_b32 s0, v252, 39
	v_readlane_b32 s1, v252, 40
	s_nop 4
	global_atomic_add v68, v3, v68, s[0:1] sc0

; __device__ __forceinline__ unsigned conv_claim(unsigned* ctr, volatile LAS unsigned* slot, int limit, int extra, unsigned known, bool peek) {
;     ...
;     if (need || opt) { T = __hip_atomic_fetch_add(ctr, 1u, __ATOMIC_RELAXED, __HIP_MEMORY_SCOPE_AGENT); known = T + 1u; if ((int)T >= TL_ALL) T = 0xffffffffu; }
;     slot[0] = T; slot[1] = need ? 0u : 1u;
;     return known;
.Lca347_join:
	s_waitcnt vmcnt(0)
	v_readfirstlane_b32 s0, v68
	s_nop 1
	v_add_u32_e32 v2, s0, v2
	s_movk_i32 s0, 0x2fa0
	v_cmp_gt_i32_e64 s[0:1], s0, v2
	v_add_u32_e32 v76, 1, v2
	s_nop 0
	v_cndmask_b32_e64 v2, -1, v2, s[0:1]

; #define LAS __attribute__((address_space(3)))
; __device__ __forceinline__ void tr_load(const TrJob& jb, int tile, int tid, f32x4 (&v)[8][2], int& k0, int& n0) {
;     const int nblk = (jb.N + 127) / 128, kt = tile / nblk, nt = tile - kt * nblk; k0 = 256 * kt; n0 = 128 * nt;
;     const int c4 = (tid & 15) + 16 * ((tid >> 6) & 1), rp = ((tid >> 4) & 3) + 4 * (tid >> 7);
;     int col = n0 + 4 * c4; col = col < jb.N - 4 ? col : jb.N - 4;
;     const float* wp = jb.W + (size_t)(k0 + 2 * rp) * jb.N + col;
; #pragma unroll
;     for (int i = 0; i < 8; ++i) { v[i][0] = *(const f32x4*)(wp + (size_t)(32 * i) * jb.N); v[i][1] = *(const f32x4*)(wp + (size_t)(32 * i + 1) * jb.N); }
;     if (jb.gain) {
; #pragma unroll
;         for (int i = 0; i < 8; ++i) { const float ga = jb.gain[k0 + 32 * i + 2 * rp], gb = jb.gain[k0 + 32 * i + 2 * rp + 1]; v[i][0] = v[i][0] * ga; v[i][1] = v[i][1] * gb; } }
; __device__ __forceinline__ unsigned conv_claim(unsigned* ctr, volatile LAS unsigned* slot, int limit, int extra, unsigned known, bool peek) {
;     if (peek) known = __hip_atomic_load(ctr, __ATOMIC_RELAXED, __HIP_MEMORY_SCOPE_AGENT);
;     const bool need = (int)known < limit, opt = !need && extra > 0 && (int)known < TL_ALL;
;     unsigned T = 0xffffffffu;
;     if (need || opt) { T = __hip_atomic_fetch_add(ctr, 1u, __ATOMIC_RELAXED, __HIP_MEMORY_SCOPE_AGENT); known = T + 1u; if ((int)T >= TL_ALL) T = 0xffffffffu; }
;     slot[0] = T; slot[1] = need ? 0u : 1u;
.LBB0_385:
	s_add_i32 s10, s34, 0x7f
	s_lshr_b32 s10, s10, 7
	v_cvt_f32_u32_e32 v2, s10
	s_sub_i32 s15, 0, s10
	s_abs_i32 s14, s40
	s_ashr_i32 s11, s40, 31
	v_rcp_iflag_f32_e32 v2, v2
	s_nop 0
	v_mul_f32_e32 v2, 0x4f7ffffe, v2
	v_cvt_u32_f32_e32 v2, v2
	s_nop 0
	v_readfirstlane_b32 s16, v2
	s_mul_i32 s15, s15, s16
	s_mul_hi_u32 s15, s16, s15
	s_add_i32 s16, s16, s15
	s_mul_hi_u32 s15, s14, s16
	s_mul_i32 s16, s15, s10
	s_sub_i32 s14, s14, s16
	s_add_i32 s17, s15, 1
	s_sub_i32 s16, s14, s10
	s_cmp_ge_u32 s14, s10
	s_cselect_b32 s15, s17, s15
	s_cselect_b32 s14, s16, s14
	s_add_i32 s16, s15, 1
	s_cmp_ge_u32 s14, s10
	s_cselect_b32 s14, s16, s15
	s_xor_b32 s14, s14, s11
	s_sub_i32 s11, s14, s11
	s_mul_i32 s10, s11, s10
	s_lshl_b32 s14, s11, 8
	s_sub_i32 s10, s40, s10
	v_add_u32_e32 v68, s14, v78
	s_lshl_b32 s15, s10, 7
	s_add_i32 s16, s34, -4
	v_or_b32_e32 v2, s15, v77
	v_mad_u64_u32 v[6:7], s[10:11], v68, s34, 0
	v_ashrrev_i32_e32 v69, 31, v68
	v_min_i32_e32 v4, s16, v2
	v_mov_b32_e32 v2, v7
	v_mad_u64_u32 v[8:9], s[10:11], v69, s34, v[2:3]
	v_mov_b32_e32 v7, v8
	v_lshl_add_u64 v[6:7], v[6:7], 2, s[12:13]
	v_ashrrev_i32_e32 v5, 31, v4
	v_lshl_add_u64 v[4:5], v[4:5], 2, v[6:7]
	s_lshl_b64 s[10:11], s[34:35], 2
	v_lshl_add_u64 v[12:13], v[4:5], 0, s[10:11]
	s_mul_i32 s12, s34, 0x7c
	s_mov_b32 s13, s35
	s_mov_b32 s63, 0
	s_and_saveexec_b64 s[86:87], s[2:3]
	s_cbranch_execz .Lca347_done
	v_readfirstlane_b32 s27, v76
	s_cmp_lg_u32 s26, 0
	s_cselect_b32 s18, 1, 0
	s_sub_i32 s18, s21, s18
	s_cmp_lt_i32 s27, s59
	s_cselect_b32 s65, 1, 0
	s_cmp_gt_i32 s18, 0
	s_cselect_b32 s18, 1, 0
	s_cmpk_lt_i32 s27, 0x2fa0
	s_cselect_b32 s67, 1, 0
	s_and_b32 s18, s18, s67
	s_or_b32 s18, s18, s65
	s_cmp_lg_u32 s18, 0
	s_cbranch_scc0 .Lca347_done
	v_mov_b32_e32 v143, 1
	v_readlane_b32 s98, v252, 39
	v_readlane_b32 s99, v252, 40
	s_mov_b32 s63, 1
	s_nop 4
	global_atomic_add v142, v3, v143, s[98:99] sc0
.Lca347_done:
	s_or_b64 exec, exec, s[86:87]
	global_load_dwordx4 v[4:7], v[4:5], off sc1 nt
	s_nop 0
	global_load_dwordx4 v[8:11], v[12:13], off sc1 nt
	v_lshl_add_u64 v[12:13], v[12:13], 0, s[12:13]
	v_lshl_add_u64 v[20:21], v[12:13], 0, s[10:11]
	global_load_dwordx4 v[12:15], v[12:13], off sc1 nt
	s_nop 0
	global_load_dwordx4 v[16:19], v[20:21], off sc1 nt
	v_lshl_add_u64 v[20:21], v[20:21], 0, s[12:13]
	v_lshl_add_u64 v[28:29], v[20:21], 0, s[10:11]
	global_load_dwordx4 v[20:23], v[20:21], off sc1 nt
	s_nop 0
	global_load_dwordx4 v[24:27], v[28:29], off sc1 nt
	v_lshl_add_u64 v[28:29], v[28:29], 0, s[12:13]
	v_lshl_add_u64 v[36:37], v[28:29], 0, s[10:11]
	v_lshl_add_u64 v[40:41], v[36:37], 0, s[12:13]
	v_lshl_add_u64 v[44:45], v[40:41], 0, s[10:11]
	v_lshl_add_u64 v[48:49], v[44:45], 0, s[12:13]
	v_lshl_add_u64 v[52:53], v[48:49], 0, s[10:11]
	v_lshl_add_u64 v[56:57], v[52:53], 0, s[12:13]
	v_lshl_add_u64 v[60:61], v[56:57], 0, s[10:11]
	v_lshl_add_u64 v[64:65], v[60:61], 0, s[12:13]
	global_load_dwordx4 v[28:31], v[28:29], off sc1 nt
	s_nop 0
	global_load_dwordx4 v[32:35], v[36:37], off sc1 nt
	s_cmp_eq_u64 s[8:9], 0
	global_load_dwordx4 v[36:39], v[40:41], off sc1 nt
	s_nop 0
	global_load_dwordx4 v[40:43], v[44:45], off sc1 nt
	s_nop 0
	global_load_dwordx4 v[44:47], v[48:49], off sc1 nt
	s_nop 0
	global_load_dwordx4 v[48:51], v[52:53], off sc1 nt
	s_nop 0
	global_load_dwordx4 v[52:55], v[56:57], off sc1 nt
	s_nop 0
	global_load_dwordx4 v[56:59], v[60:61], off sc1 nt
	s_nop 0
	global_load_dwordx4 v[60:63], v[64:65], off sc1 nt
	v_lshl_add_u64 v[64:65], v[64:65], 0, s[10:11]
	global_load_dwordx4 v[64:67], v[64:65], off sc1 nt
	s_cbranch_scc1 .LBB0_387
	v_lshl_add_u64 v[70:71], v[68:69], 2, s[8:9]
	global_load_dwordx2 v[70:71], v[70:71], off
	s_waitcnt vmcnt(0)
	v_pk_mul_f32 v[6:7], v[6:7], v[70:71] op_sel_hi:[1,0]
	v_pk_mul_f32 v[4:5], v[4:5], v[70:71] op_sel_hi:[1,0]
	v_pk_mul_f32 v[10:11], v[10:11], v[70:71] op_sel:[0,1]
	v_pk_mul_f32 v[8:9], v[8:9], v[70:71] op_sel:[0,1]
	v_add_u32_e32 v70, 32, v68
	v_ashrrev_i32_e32 v71, 31, v70
	v_lshl_add_u64 v[70:71], v[70:71], 2, s[8:9]
	global_load_dwordx2 v[70:71], v[70:71], off
	s_waitcnt vmcnt(0)
	v_pk_mul_f32 v[14:15], v[14:15], v[70:71] op_sel_hi:[1,0]
	v_pk_mul_f32 v[12:13], v[12:13], v[70:71] op_sel_hi:[1,0]
	v_pk_mul_f32 v[18:19], v[18:19], v[70:71] op_sel:[0,1]
	v_pk_mul_f32 v[16:17], v[16:17], v[70:71] op_sel:[0,1]
	v_add_u32_e32 v70, 64, v68
	v_ashrrev_i32_e32 v71, 31, v70
	v_lshl_add_u64 v[70:71], v[70:71], 2, s[8:9]
	global_load_dwordx2 v[70:71], v[70:71], off
	s_waitcnt vmcnt(0)
	v_pk_mul_f32 v[22:23], v[22:23], v[70:71] op_sel_hi:[1,0]
	v_pk_mul_f32 v[20:21], v[20:21], v[70:71] op_sel_hi:[1,0]
	v_pk_mul_f32 v[26:27], v[26:27], v[70:71] op_sel:[0,1]
	v_pk_mul_f32 v[24:25], v[24:25], v[70:71] op_sel:[0,1]
	v_add_u32_e32 v70, 0x60, v68
	v_ashrrev_i32_e32 v71, 31, v70
	v_lshl_add_u64 v[70:71], v[70:71], 2, s[8:9]
	global_load_dwordx2 v[70:71], v[70:71], off
	s_waitcnt vmcnt(0)
	v_pk_mul_f32 v[30:31], v[30:31], v[70:71] op_sel_hi:[1,0]
	v_pk_mul_f32 v[28:29], v[28:29], v[70:71] op_sel_hi:[1,0]
	v_pk_mul_f32 v[34:35], v[34:35], v[70:71] op_sel:[0,1]
	v_pk_mul_f32 v[32:33], v[32:33], v[70:71] op_sel:[0,1]
	v_add_u32_e32 v70, 0x80, v68
	v_ashrrev_i32_e32 v71, 31, v70
	v_lshl_add_u64 v[70:71], v[70:71], 2, s[8:9]
	global_load_dwordx2 v[70:71], v[70:71], off
	s_waitcnt vmcnt(0)
	v_pk_mul_f32 v[38:39], v[38:39], v[70:71] op_sel_hi:[1,0]
	v_pk_mul_f32 v[36:37], v[36:37], v[70:71] op_sel_hi:[1,0]
	v_pk_mul_f32 v[42:43], v[42:43], v[70:71] op_sel:[0,1]
	v_pk_mul_f32 v[40:41], v[40:41], v[70:71] op_sel:[0,1]
	v_add_u32_e32 v70, 0xa0, v68
	v_ashrrev_i32_e32 v71, 31, v70
	v_lshl_add_u64 v[70:71], v[70:71], 2, s[8:9]
	global_load_dwordx2 v[70:71], v[70:71], off
	s_waitcnt vmcnt(0)
	v_pk_mul_f32 v[46:47], v[46:47], v[70:71] op_sel_hi:[1,0]
	v_pk_mul_f32 v[44:45], v[44:45], v[70:71] op_sel_hi:[1,0]
	v_pk_mul_f32 v[50:51], v[50:51], v[70:71] op_sel:[0,1]
	v_pk_mul_f32 v[48:49], v[48:49], v[70:71] op_sel:[0,1]
	v_add_u32_e32 v70, 0xc0, v68
	v_add_u32_e32 v68, 0xe0, v68
	v_ashrrev_i32_e32 v71, 31, v70
	v_ashrrev_i32_e32 v69, 31, v68
	v_lshl_add_u64 v[70:71], v[70:71], 2, s[8:9]
	v_lshl_add_u64 v[68:69], v[68:69], 2, s[8:9]
	global_load_dwordx2 v[70:71], v[70:71], off
	s_nop 0
	global_load_dwordx2 v[68:69], v[68:69], off
	s_waitcnt vmcnt(1)
	v_pk_mul_f32 v[54:55], v[54:55], v[70:71] op_sel_hi:[1,0]
	v_pk_mul_f32 v[52:53], v[52:53], v[70:71] op_sel_hi:[1,0]
	v_pk_mul_f32 v[58:59], v[58:59], v[70:71] op_sel:[0,1]
	v_pk_mul_f32 v[56:57], v[56:57], v[70:71] op_sel:[0,1]
	s_waitcnt vmcnt(0)
	v_pk_mul_f32 v[62:63], v[62:63], v[68:69] op_sel_hi:[1,0]
	v_pk_mul_f32 v[60:61], v[60:61], v[68:69] op_sel_hi:[1,0]
	v_pk_mul_f32 v[66:67], v[66:67], v[68:69] op_sel:[0,1]
	v_pk_mul_f32 v[64:65], v[64:65], v[68:69] op_sel:[0,1]

; #define LAS __attribute__((address_space(3)))
; __device__ __forceinline__ unsigned pk2(float lo, float hi) { return f2bf(lo) | (f2bf(hi) << 16); }
; __device__ __forceinline__ void tr_to_lds(LAS unsigned* T, int tid, const f32x4 (&v)[8][2]) {
;     const int c4 = (tid & 15) + 16 * ((tid >> 6) & 1), rp = ((tid >> 4) & 3) + 4 * (tid >> 7);
; #pragma unroll
;     for (int i = 0; i < 8; ++i)
; #pragma unroll
;         for (int j = 0; j < 4; ++j) T[(4 * c4 + j) * 132 + 16 * i + rp] = pk2(v[i][0][j], v[i][1][j]);
; __device__ __forceinline__ void conv_until(const Args& A, LAS unsigned char* lds, int limit, int extra) {
;     ...
;     f32x4 v[8][2]; TrJob jb; int t, k0, n0;
;     conv_job(A, (int)T, jb, t); tr_load(jb, t, tid, v, k0, n0);
; #pragma unroll 1
;     for (;;) {
;         tr_to_lds(Tl, tid, v);
.LBB0_1039:
	v_and_b32_e32 v69, -4, v71
	v_ashrrev_i32_e32 v71, 4, v2
	v_bfe_u32 v68, v2, 4, 2
	s_cmp_lg_u32 s16, 0
	v_bfi_b32 v71, -8, v71, v2
	v_lshrrev_b32_e32 v2, 3, v2
	s_cselect_b64 s[4:5], -1, 0
	v_lshlrev_b32_e32 v68, 2, v68
	v_lshlrev_b32_e32 v69, 2, v69
	v_and_or_b32 v79, v2, 7, v70
	s_cmp_lg_u64 s[4:5], 0
	v_readlane_b32 s4, v254, 37
	v_add3_u32 v68, 0, v68, v69
	v_mul_u32_u24_e32 v69, 0x210, v77
	v_lshl_add_u32 v2, v71, 4, 0
	v_mul_u32_u24_e32 v70, 0x210, v79
	s_subb_u32 s21, s4, 0
	v_lshlrev_b32_e32 v80, 3, v71
	v_or_b32_e32 v81, 8, v79
	v_or_b32_e32 v82, 16, v79
	v_or_b32_e32 v83, 24, v79
	v_or_b32_e32 v84, 32, v79
	v_or_b32_e32 v85, 40, v79
	v_or_b32_e32 v86, 48, v79
	v_or_b32_e32 v87, 56, v79
	v_add_u32_e32 v88, v68, v69
	v_add_u32_e32 v89, v2, v70
	s_mov_b32 s32, 0
	s_branch .LBB0_1041

; #define LAS __attribute__((address_space(3)))
; __device__ __forceinline__ unsigned pk2(float lo, float hi) { return f2bf(lo) | (f2bf(hi) << 16); }
; __device__ __forceinline__ void tr_to_lds(LAS unsigned* T, int tid, const f32x4 (&v)[8][2]) {
;     const int c4 = (tid & 15) + 16 * ((tid >> 6) & 1), rp = ((tid >> 4) & 3) + 4 * (tid >> 7);
; #pragma unroll
;     for (int i = 0; i < 8; ++i)
; #pragma unroll
;         for (int j = 0; j < 4; ++j) T[(4 * c4 + j) * 132 + 16 * i + rp] = pk2(v[i][0][j], v[i][1][j]);
; __device__ __forceinline__ void conv_until(const Args& A, LAS unsigned char* lds, int limit, int extra) {
;     ...
;     for (;;) {
;         tr_to_lds(Tl, tid, v);
;         if (tid == 0) known = conv_claim(ctr, slot, limit, extra, known, false);
.LBB0_1041:
	s_waitcnt vmcnt(15)
	v_bfe_u32 v2, v4, 16, 1
	v_add3_u32 v2, v4, v2, s81
	s_waitcnt vmcnt(14)
	v_bfe_u32 v68, v8, 16, 1
	v_lshrrev_b32_e32 v2, 16, v2
	v_add3_u32 v68, v8, v68, s81
	v_and_or_b32 v2, v68, s82, v2
	v_bfe_u32 v68, v5, 16, 1
	v_add3_u32 v68, v5, v68, s81
	v_bfe_u32 v69, v9, 16, 1
	v_lshrrev_b32_e32 v68, 16, v68
	v_add3_u32 v69, v9, v69, s81
	v_and_or_b32 v68, v69, s82, v68
	v_bfe_u32 v69, v6, 16, 1
	v_add3_u32 v69, v6, v69, s81
	v_bfe_u32 v70, v10, 16, 1
	v_lshrrev_b32_e32 v69, 16, v69
	v_add3_u32 v70, v10, v70, s81
	v_and_or_b32 v69, v70, s82, v69
	v_bfe_u32 v70, v7, 16, 1
	v_add3_u32 v70, v7, v70, s81
	v_bfe_u32 v71, v11, 16, 1
	v_lshrrev_b32_e32 v70, 16, v70
	v_add3_u32 v71, v11, v71, s81
	v_and_or_b32 v70, v71, s82, v70
	s_waitcnt vmcnt(13)
	v_bfe_u32 v71, v12, 16, 1
	v_add3_u32 v71, v12, v71, s81
	s_waitcnt vmcnt(12)
	v_bfe_u32 v72, v16, 16, 1
	v_lshrrev_b32_e32 v71, 16, v71
	v_add3_u32 v72, v16, v72, s81
	v_and_or_b32 v71, v72, s82, v71
	ds_write2_b32 v88, v2, v71 offset1:16
	v_bfe_u32 v2, v13, 16, 1
	v_add3_u32 v2, v13, v2, s81
	v_bfe_u32 v71, v17, 16, 1
	v_lshrrev_b32_e32 v2, 16, v2
	v_add3_u32 v71, v17, v71, s81
	v_and_or_b32 v2, v71, s82, v2
	ds_write2_b32 v88, v68, v2 offset0:132 offset1:148
	v_bfe_u32 v2, v14, 16, 1
	v_add3_u32 v2, v14, v2, s81
	v_bfe_u32 v68, v18, 16, 1
	v_lshrrev_b32_e32 v2, 16, v2
	v_add3_u32 v68, v18, v68, s81
	v_and_or_b32 v2, v68, s82, v2
	v_add_u32_e32 v68, 0x400, v88
	ds_write2_b32 v68, v69, v2 offset0:8 offset1:24
	v_bfe_u32 v2, v15, 16, 1
	v_add3_u32 v2, v15, v2, s81
	v_bfe_u32 v69, v19, 16, 1
	v_lshrrev_b32_e32 v2, 16, v2
	v_add3_u32 v69, v19, v69, s81
	v_and_or_b32 v2, v69, s82, v2
	ds_write2_b32 v68, v70, v2 offset0:140 offset1:156
	s_waitcnt vmcnt(11)
	v_bfe_u32 v2, v20, 16, 1
	v_add3_u32 v2, v20, v2, s81
	s_waitcnt vmcnt(10)
	v_bfe_u32 v69, v24, 16, 1
	v_lshrrev_b32_e32 v2, 16, v2
	v_add3_u32 v69, v24, v69, s81
	v_and_or_b32 v2, v69, s82, v2
	v_bfe_u32 v69, v21, 16, 1
	v_add3_u32 v69, v21, v69, s81
	v_bfe_u32 v70, v25, 16, 1
	v_lshrrev_b32_e32 v69, 16, v69
	v_add3_u32 v70, v25, v70, s81
	v_and_or_b32 v69, v70, s82, v69
	v_bfe_u32 v70, v22, 16, 1
	v_add3_u32 v70, v22, v70, s81
	v_bfe_u32 v71, v26, 16, 1
	v_lshrrev_b32_e32 v70, 16, v70
	v_add3_u32 v71, v26, v71, s81
	v_and_or_b32 v70, v71, s82, v70
	v_bfe_u32 v71, v23, 16, 1
	v_add3_u32 v71, v23, v71, s81
	v_bfe_u32 v72, v27, 16, 1
	v_lshrrev_b32_e32 v71, 16, v71
	v_add3_u32 v72, v27, v72, s81
	v_and_or_b32 v71, v72, s82, v71
	s_waitcnt vmcnt(9)
	v_bfe_u32 v72, v28, 16, 1
	v_add3_u32 v72, v28, v72, s81
	s_waitcnt vmcnt(8)
	v_bfe_u32 v73, v32, 16, 1
	v_lshrrev_b32_e32 v72, 16, v72
	v_add3_u32 v73, v32, v73, s81
	v_and_or_b32 v72, v73, s82, v72
	ds_write2_b32 v88, v2, v72 offset0:32 offset1:48
	v_bfe_u32 v2, v29, 16, 1
	v_add3_u32 v2, v29, v2, s81
	v_bfe_u32 v72, v33, 16, 1
	v_lshrrev_b32_e32 v2, 16, v2
	v_add3_u32 v72, v33, v72, s81
	v_and_or_b32 v2, v72, s82, v2
	ds_write2_b32 v88, v69, v2 offset0:164 offset1:180
	v_bfe_u32 v2, v30, 16, 1
	v_add3_u32 v2, v30, v2, s81
	v_bfe_u32 v69, v34, 16, 1
	v_lshrrev_b32_e32 v2, 16, v2
	v_add3_u32 v69, v34, v69, s81
	v_and_or_b32 v2, v69, s82, v2
	ds_write2_b32 v68, v70, v2 offset0:40 offset1:56
	v_bfe_u32 v2, v31, 16, 1
	v_add3_u32 v2, v31, v2, s81
	v_bfe_u32 v69, v35, 16, 1
	v_lshrrev_b32_e32 v2, 16, v2
	v_add3_u32 v69, v35, v69, s81
	v_and_or_b32 v2, v69, s82, v2
	ds_write2_b32 v68, v71, v2 offset0:172 offset1:188
	s_waitcnt vmcnt(7)
	v_bfe_u32 v2, v36, 16, 1
	v_add3_u32 v2, v36, v2, s81
	s_waitcnt vmcnt(6)
	v_bfe_u32 v69, v40, 16, 1
	v_lshrrev_b32_e32 v2, 16, v2
	v_add3_u32 v69, v40, v69, s81
	v_and_or_b32 v2, v69, s82, v2
	v_bfe_u32 v69, v37, 16, 1
	v_add3_u32 v69, v37, v69, s81
	v_bfe_u32 v70, v41, 16, 1
	v_lshrrev_b32_e32 v69, 16, v69
	v_add3_u32 v70, v41, v70, s81
	v_and_or_b32 v69, v70, s82, v69
	v_bfe_u32 v70, v38, 16, 1
	v_add3_u32 v70, v38, v70, s81
	v_bfe_u32 v71, v42, 16, 1
	v_lshrrev_b32_e32 v70, 16, v70
	v_add3_u32 v71, v42, v71, s81
	v_and_or_b32 v70, v71, s82, v70
	v_bfe_u32 v71, v39, 16, 1
	v_add3_u32 v71, v39, v71, s81
	v_bfe_u32 v72, v43, 16, 1
	v_lshrrev_b32_e32 v71, 16, v71
	v_add3_u32 v72, v43, v72, s81
	v_and_or_b32 v71, v72, s82, v71
	s_waitcnt vmcnt(5)
	v_bfe_u32 v72, v44, 16, 1
	v_add3_u32 v72, v44, v72, s81
	s_waitcnt vmcnt(4)
	v_bfe_u32 v73, v48, 16, 1
	v_lshrrev_b32_e32 v72, 16, v72
	v_add3_u32 v73, v48, v73, s81
	v_and_or_b32 v72, v73, s82, v72
	ds_write2_b32 v88, v2, v72 offset0:64 offset1:80
	v_bfe_u32 v2, v45, 16, 1
	v_add3_u32 v2, v45, v2, s81
	v_bfe_u32 v72, v49, 16, 1
	v_lshrrev_b32_e32 v2, 16, v2
	v_add3_u32 v72, v49, v72, s81
	v_and_or_b32 v2, v72, s82, v2
	ds_write2_b32 v88, v69, v2 offset0:196 offset1:212
	v_bfe_u32 v2, v46, 16, 1
	v_add3_u32 v2, v46, v2, s81
	v_bfe_u32 v69, v50, 16, 1
	v_lshrrev_b32_e32 v2, 16, v2
	v_add3_u32 v69, v50, v69, s81
	v_and_or_b32 v2, v69, s82, v2
	ds_write2_b32 v68, v70, v2 offset0:72 offset1:88
	v_bfe_u32 v2, v47, 16, 1
	v_add3_u32 v2, v47, v2, s81
	v_bfe_u32 v69, v51, 16, 1
	v_lshrrev_b32_e32 v2, 16, v2
	v_add3_u32 v69, v51, v69, s81
	v_and_or_b32 v2, v69, s82, v2
	ds_write2_b32 v68, v71, v2 offset0:204 offset1:220
	s_waitcnt vmcnt(3)
	v_bfe_u32 v2, v52, 16, 1
	v_add3_u32 v2, v52, v2, s81
	s_waitcnt vmcnt(2)
	v_bfe_u32 v69, v56, 16, 1
	v_lshrrev_b32_e32 v2, 16, v2
	v_add3_u32 v69, v56, v69, s81
	v_and_or_b32 v2, v69, s82, v2
	v_bfe_u32 v69, v53, 16, 1
	v_add3_u32 v69, v53, v69, s81
	v_bfe_u32 v70, v57, 16, 1
	v_lshrrev_b32_e32 v69, 16, v69
	v_add3_u32 v70, v57, v70, s81
	v_and_or_b32 v69, v70, s82, v69
	v_bfe_u32 v70, v54, 16, 1
	v_add3_u32 v70, v54, v70, s81
	v_bfe_u32 v71, v58, 16, 1
	v_lshrrev_b32_e32 v70, 16, v70
	v_add3_u32 v71, v58, v71, s81
	v_and_or_b32 v70, v71, s82, v70
	v_bfe_u32 v71, v55, 16, 1
	v_add3_u32 v71, v55, v71, s81
	v_bfe_u32 v72, v59, 16, 1
	v_lshrrev_b32_e32 v71, 16, v71
	v_add3_u32 v72, v59, v72, s81
	v_and_or_b32 v71, v72, s82, v71
	s_waitcnt vmcnt(1)
	v_bfe_u32 v72, v60, 16, 1
	v_add3_u32 v72, v60, v72, s81
	s_waitcnt vmcnt(0)
	v_bfe_u32 v73, v64, 16, 1
	v_lshrrev_b32_e32 v72, 16, v72
	v_add3_u32 v73, v64, v73, s81
	v_and_or_b32 v72, v73, s82, v72
	ds_write2_b32 v88, v2, v72 offset0:96 offset1:112
	v_bfe_u32 v2, v61, 16, 1
	v_add3_u32 v2, v61, v2, s81
	v_bfe_u32 v72, v65, 16, 1
	v_lshrrev_b32_e32 v2, 16, v2
	v_add3_u32 v72, v65, v72, s81
	v_and_or_b32 v2, v72, s82, v2
	ds_write2_b32 v88, v69, v2 offset0:228 offset1:244
	v_bfe_u32 v2, v62, 16, 1
	v_add3_u32 v2, v62, v2, s81
	v_bfe_u32 v69, v66, 16, 1
	v_lshrrev_b32_e32 v2, 16, v2
	v_add3_u32 v69, v66, v69, s81
	v_and_or_b32 v2, v69, s82, v2
	ds_write2_b32 v68, v70, v2 offset0:104 offset1:120
	v_bfe_u32 v2, v63, 16, 1
	v_add3_u32 v2, v63, v2, s81
	v_bfe_u32 v69, v67, 16, 1
	v_lshrrev_b32_e32 v2, 16, v2
	v_add3_u32 v69, v67, v69, s81
	s_mov_b32 s24, s15
	s_mov_b32 s28, s14
	s_mov_b64 s[6:7], s[0:1]
	s_mov_b32 s22, s19
	s_mov_b32 s25, s34
	s_mov_b32 s23, s20
	v_and_or_b32 v2, v69, s82, v2
	ds_write2_b32 v68, v71, v2 offset0:236 offset1:252
	s_and_saveexec_b64 s[4:5], s[2:3]
	s_cbranch_execz .LBB0_1047
; #define LAS __attribute__((address_space(3)))
; __device__ __forceinline__ unsigned conv_claim(unsigned* ctr, volatile LAS unsigned* slot, int limit, int extra, unsigned known, bool peek) {
;     if (peek) known = __hip_atomic_load(ctr, __ATOMIC_RELAXED, __HIP_MEMORY_SCOPE_AGENT);
;     const bool need = (int)known < limit, opt = !need && extra > 0 && (int)known < TL_ALL;
;     unsigned T = 0xffffffffu;
;     if (need || opt) { T = __hip_atomic_fetch_add(ctr, 1u, __ATOMIC_RELAXED, __HIP_MEMORY_SCOPE_AGENT); known = T + 1u; if ((int)T >= TL_ALL) T = 0xffffffffu; }
;     slot[0] = T; slot[1] = need ? 0u : 1u;
;     return known;
	s_cmp_lg_u32 s32, 0
	s_cbranch_scc0 .Lca1041_orig
	s_mov_b32 s32, 0
	s_mov_b64 s[8:9], exec
	s_cmp_lg_u32 s65, 0
	s_cselect_b64 vcc, exec, 0
	v_mov_b32_e32 v2, 0
	s_waitcnt vmcnt(0)
	v_mov_b32_e32 v68, v142
	s_branch .Lca1041_join
.Lca1041_orig:
	s_cmp_gt_i32 s21, 0
	s_movk_i32 s0, 0x2fa0
	s_cselect_b64 s[8:9], -1, 0
	v_cmp_gt_i32_e64 s[0:1], s0, v76
	v_cmp_gt_i32_e32 vcc, s18, v76
	s_and_b64 s[0:1], s[0:1], s[8:9]
	s_or_b64 s[0:1], vcc, s[0:1]
	v_mov_b32_e32 v2, -1
	s_and_saveexec_b64 s[8:9], s[0:1]
	s_cbranch_execz .LBB0_1046
	s_mov_b64 s[12:13], exec
	v_mbcnt_lo_u32_b32 v2, s12, 0
	v_mbcnt_hi_u32_b32 v2, s13, v2
	v_cmp_eq_u32_e64 s[0:1], 0, v2
	s_and_saveexec_b64 s[10:11], s[0:1]
	s_cbranch_execz .LBB0_1045
	s_bcnt1_i32_b64 s0, s[12:13]
	v_mov_b32_e32 v68, s0
	v_readlane_b32 s0, v252, 39
	v_readlane_b32 s1, v252, 40
	s_nop 4
	global_atomic_add v68, v3, v68, s[0:1] sc0

; #define LAS __attribute__((address_space(3)))
; __device__ __forceinline__ void tr_load(const TrJob& jb, int tile, int tid, f32x4 (&v)[8][2], int& k0, int& n0) {
;     const int nblk = (jb.N + 127) / 128, kt = tile / nblk, nt = tile - kt * nblk; k0 = 256 * kt; n0 = 128 * nt;
;     const int c4 = (tid & 15) + 16 * ((tid >> 6) & 1), rp = ((tid >> 4) & 3) + 4 * (tid >> 7);
;     int col = n0 + 4 * c4; col = col < jb.N - 4 ? col : jb.N - 4;
;     const float* wp = jb.W + (size_t)(k0 + 2 * rp) * jb.N + col;
; #pragma unroll
; __device__ __forceinline__ unsigned conv_claim(unsigned* ctr, volatile LAS unsigned* slot, int limit, int extra, unsigned known, bool peek) {
;     if (peek) known = __hip_atomic_load(ctr, __ATOMIC_RELAXED, __HIP_MEMORY_SCOPE_AGENT);
;     const bool need = (int)known < limit, opt = !need && extra > 0 && (int)known < TL_ALL;
;     unsigned T = 0xffffffffu;
;     if (need || opt) { T = __hip_atomic_fetch_add(ctr, 1u, __ATOMIC_RELAXED, __HIP_MEMORY_SCOPE_AGENT); known = T + 1u; if ((int)T >= TL_ALL) T = 0xffffffffu; }
.LBB0_1079:
	s_add_i32 s10, s34, 0x7f
	s_lshr_b32 s10, s10, 7
	v_cvt_f32_u32_e32 v2, s10
	s_sub_i32 s15, 0, s10
	s_abs_i32 s14, s30
	s_ashr_i32 s11, s30, 31
	v_rcp_iflag_f32_e32 v2, v2
	s_nop 0
	v_mul_f32_e32 v2, 0x4f7ffffe, v2
	v_cvt_u32_f32_e32 v2, v2
	s_nop 0
	v_readfirstlane_b32 s16, v2
	s_mul_i32 s15, s15, s16
	s_mul_hi_u32 s15, s16, s15
	s_add_i32 s16, s16, s15
	s_mul_hi_u32 s15, s14, s16
	s_mul_i32 s16, s15, s10
	s_sub_i32 s14, s14, s16
	s_add_i32 s17, s15, 1
	s_sub_i32 s16, s14, s10
	s_cmp_ge_u32 s14, s10
	s_cselect_b32 s15, s17, s15
	s_cselect_b32 s14, s16, s14
	s_add_i32 s16, s15, 1
	s_cmp_ge_u32 s14, s10
	s_cselect_b32 s14, s16, s15
	s_xor_b32 s14, s14, s11
	s_sub_i32 s11, s14, s11
	s_mul_i32 s10, s11, s10
	s_lshl_b32 s14, s11, 8
	s_sub_i32 s10, s30, s10
	v_add_u32_e32 v68, s14, v78
	s_lshl_b32 s15, s10, 7
	s_add_i32 s16, s34, -4
	v_or_b32_e32 v2, s15, v77
	v_mad_u64_u32 v[6:7], s[10:11], v68, s34, 0
	v_ashrrev_i32_e32 v69, 31, v68
	v_min_i32_e32 v4, s16, v2
	v_mov_b32_e32 v2, v7
	v_mad_u64_u32 v[8:9], s[10:11], v69, s34, v[2:3]
	v_mov_b32_e32 v7, v8
	v_lshl_add_u64 v[6:7], v[6:7], 2, s[12:13]
	v_ashrrev_i32_e32 v5, 31, v4
	v_lshl_add_u64 v[4:5], v[4:5], 2, v[6:7]
	s_lshl_b64 s[10:11], s[34:35], 2
	v_lshl_add_u64 v[12:13], v[4:5], 0, s[10:11]
	s_mul_i32 s12, s34, 0x7c
	s_mov_b32 s13, s35
	s_mov_b32 s32, 0
	s_and_saveexec_b64 s[86:87], s[2:3]
	s_cbranch_execz .Lca1041_done
	v_readfirstlane_b32 s27, v76
	s_cmp_lg_u32 s26, 0
	s_cselect_b32 s38, 1, 0
	s_sub_i32 s38, s21, s38
	s_cmp_lt_i32 s27, s18
	s_cselect_b32 s65, 1, 0
	s_cmp_gt_i32 s38, 0
	s_cselect_b32 s38, 1, 0
	s_cmpk_lt_i32 s27, 0x2fa0
	s_cselect_b32 s67, 1, 0
	s_and_b32 s38, s38, s67
	s_or_b32 s38, s38, s65
	s_cmp_lg_u32 s38, 0
	s_cbranch_scc0 .Lca1041_done
	v_mov_b32_e32 v143, 1
	v_readlane_b32 s98, v252, 39
	v_readlane_b32 s99, v252, 40
	s_mov_b32 s32, 1
	s_nop 4
	global_atomic_add v142, v3, v143, s[98:99] sc0
